# 4/4 LDS-DMA staging balance also in the P4 Cq and P3 K-loops; SGPR-base DMA form in P4 Cq and the P7 half-unit loop
# speedup vs baseline: 1.0066x; 1.0013x over previous
; #define PG8_STAGE(bufoff, gbase, voff) do { _Pragma("unroll") for (int _i = 0; _i < 2; ++_i) \
;         __builtin_amdgcn_global_load_lds((const unsigned*)((const char*)(gbase) + (voff)[_i]), (PG8_LAS unsigned*)(lds + (bufoff) + ldsw + _i * 8192), 16, 0, 0); } while (0)
; #define PG8_LDA(dst, b, h) do { _Pragma("unroll") for (int m = 0; m < 4; ++m) _Pragma("unroll") for (int k = 0; k < 2; ++k) dst[m][k] = *(const PG8_LAS bf16x8*)(lds + PG8_SA(b, h) + aoff + m * 2048 + k * 1024); } while (0)
; #define PG8_LDB(dst, b, h) do { _Pragma("unroll") for (int n = 0; n < 2; ++n) _Pragma("unroll") for (int k = 0; k < 2; ++k) dst[n][k] = *(const PG8_LAS bf16x8*)(lds + PG8_SB(b, h) + boff + n * 2048 + k * 1024); } while (0)
; #define PG8_WAIT_V(n) asm volatile("s_waitcnt vmcnt(" #n ")" ::: "memory")
; #define PG8_WAIT_L(n) asm volatile("s_waitcnt lgkmcnt(" #n ")" ::: "memory")
; #define PG8_BAR __builtin_amdgcn_s_barrier()
; #define PG8_SCHED __builtin_amdgcn_sched_barrier(0)
; template <class Epi, class Sched, bool ALIGN_EPI = false, bool SP2 = false>
; __device__ __forceinline__ void gemm_phase(PG8_LAS unsigned char* lds, const Gemm g, const Sched& S, const Epi& E) {
;     ...
;         const char* nA = has_next ? (const char*)g.A + (size_t)nxt.pm * tstepA : cA; const char* nB = has_next ? (const char*)g.Bt + (size_t)nxt.pn * tstepB : cB;
;         for (int t = 0; t < nt; t += 2) {
;             const bool last = (t == nt - 2);
;             if constexpr (Epi::HAS_MID) { if (t == E.mid_t) E.mid(acc, cur, wr, wc, fr, fq); }
;             const char* a1 = cA + (size_t)(t + 1) * kstep;
;             const char* a2 = last ? nA : cA + (size_t)(t + 2) * kstep; const char* b2 = last ? nB : cB + (size_t)(t + 2) * kstep;
;             const char* a3 = a2 + kstep; const char* b3 = b2 + kstep;
;             if (last && has_next) S.a_ready(nxt);
;             if constexpr (SP2) {
;             PG8_LDB(B0, 0, 0); PG8_LDB(B1, 0, 1); PG8_SCHED; PG8_LDA(At, 0, 0); PG8_STAGE(PG8_SA(1, 1), a1 + hstepA, voffA);
;             PG8_WAIT_V(8); PG8_WAIT_L(0); PG8_BAR; PG8_MMA(0, 0, At, B0); PG8_MMA(0, 1, At, B1); PG8_BAR; PG8_SCHED;
;             PG8_LDA(At, 0, 1); PG8_STAGE(PG8_SB(0, 0), b2, voffB); PG8_STAGE(PG8_SB(0, 1), b2 + hstepB, voffB); PG8_STAGE(PG8_SA(0, 0), a2, voffA);
;             PG8_WAIT_V(8); PG8_WAIT_L(0); PG8_BAR; PG8_MMA(1, 0, At, B0); PG8_MMA(1, 1, At, B1); PG8_BAR; PG8_SCHED;
.LBB0_1217:
	v_add_u32_e32 v1, s57, v154
	ds_read_b128 v[158:161], v1
	ds_read_b128 v[162:165], v1 offset:1024
	ds_read_b128 v[166:169], v1 offset:2048
	ds_read_b128 v[170:173], v1 offset:3072
	v_add_u32_e32 v1, s58, v154
	s_add_u32 s42, s78, s18
	ds_read_b128 v[174:177], v1
	ds_read_b128 v[178:181], v1 offset:1024
	ds_read_b128 v[182:185], v1 offset:2048
	ds_read_b128 v[186:189], v1 offset:3072
	s_addc_u32 s43, s79, s19
	s_add_u32 s42, s42, 0x100
	s_addc_u32 s43, s43, 0
	s_add_u32 s69, s66, s18
	s_addc_u32 s70, s67, s19
	s_cmpk_eq_i32 s18, 0xf00
	s_cselect_b32 s43, s62, s43
	s_cselect_b32 s42, s63, s42
	s_cselect_b32 vcc_hi, s51, s70
	s_cselect_b32 vcc_lo, s65, s69
	v_lshl_add_u64 v[2:3], v[148:149], 0, s[18:19]
	s_add_i32 m0, s5, 0xc000
	ds_read_b128 v[190:193], v156
	ds_read_b128 v[194:197], v156 offset:1024
	ds_read_b128 v[198:201], v156 offset:2048
	ds_read_b128 v[202:205], v156 offset:3072
	ds_read_b128 v[206:209], v156 offset:4096
	ds_read_b128 v[210:213], v156 offset:5120
	ds_read_b128 v[214:217], v156 offset:6144
	ds_read_b128 v[218:221], v156 offset:7168
	s_add_u32 s98, s78, s18
	s_addc_u32 s99, s79, s19
	s_add_u32 s98, s98, 0x80
	s_addc_u32 s99, s99, 0
	s_mov_b32 m0, s47
	s_nop 0
	global_load_lds_dwordx4 v132, s[98:99]
	s_mov_b32 m0, s56
	s_nop 0
	global_load_lds_dwordx4 v136, s[98:99]
	s_add_i32 m0, s5, 0xc000
	s_nop 0
	global_load_lds_dwordx4 v[2:3], off
	v_lshl_add_u64 v[2:3], v[150:151], 0, s[18:19]
	s_add_i32 m0, s5, 0xe000
	s_nop 0
	global_load_lds_dwordx4 v[2:3], off
	s_waitcnt vmcnt(8)
	s_waitcnt lgkmcnt(0)
	s_barrier
	s_setprio 1
	s_waitcnt lgkmcnt(0)
	v_mfma_f32_16x16x32_bf16 v[128:131], v[158:161], v[190:193], v[128:131]
	v_mfma_f32_16x16x32_bf16 v[124:127], v[166:169], v[190:193], v[124:127]
	v_mfma_f32_16x16x32_bf16 v[112:115], v[158:161], v[198:201], v[112:115]
	v_mfma_f32_16x16x32_bf16 v[108:111], v[166:169], v[198:201], v[108:111]
	v_mfma_f32_16x16x32_bf16 v[96:99], v[158:161], v[206:209], v[96:99]
	v_mfma_f32_16x16x32_bf16 v[92:95], v[166:169], v[206:209], v[92:95]
	v_mfma_f32_16x16x32_bf16 v[80:83], v[158:161], v[214:217], v[80:83]
	v_mfma_f32_16x16x32_bf16 v[76:79], v[166:169], v[214:217], v[76:79]
	v_mfma_f32_16x16x32_bf16 v[128:131], v[162:165], v[194:197], v[128:131]
	v_mfma_f32_16x16x32_bf16 v[124:127], v[170:173], v[194:197], v[124:127]
	v_mfma_f32_16x16x32_bf16 v[112:115], v[162:165], v[202:205], v[112:115]
	v_mfma_f32_16x16x32_bf16 v[108:111], v[170:173], v[202:205], v[108:111]
	v_mfma_f32_16x16x32_bf16 v[96:99], v[162:165], v[210:213], v[96:99]
	v_mfma_f32_16x16x32_bf16 v[92:95], v[170:173], v[210:213], v[92:95]
	v_mfma_f32_16x16x32_bf16 v[80:83], v[162:165], v[218:221], v[80:83]
	v_mfma_f32_16x16x32_bf16 v[76:79], v[170:173], v[218:221], v[76:79]
	s_setprio 0
	s_setprio 1
	v_mfma_f32_16x16x32_bf16 v[120:123], v[174:177], v[190:193], v[120:123]
	v_mfma_f32_16x16x32_bf16 v[116:119], v[182:185], v[190:193], v[116:119]
	v_mfma_f32_16x16x32_bf16 v[104:107], v[174:177], v[198:201], v[104:107]
	v_mfma_f32_16x16x32_bf16 v[100:103], v[182:185], v[198:201], v[100:103]
	v_mfma_f32_16x16x32_bf16 v[88:91], v[174:177], v[206:209], v[88:91]
	v_mfma_f32_16x16x32_bf16 v[84:87], v[182:185], v[206:209], v[84:87]
	v_mfma_f32_16x16x32_bf16 v[72:75], v[174:177], v[214:217], v[72:75]
	v_mfma_f32_16x16x32_bf16 v[68:71], v[182:185], v[214:217], v[68:71]
	v_mfma_f32_16x16x32_bf16 v[120:123], v[178:181], v[194:197], v[120:123]
	v_mfma_f32_16x16x32_bf16 v[116:119], v[186:189], v[194:197], v[116:119]
	v_mfma_f32_16x16x32_bf16 v[104:107], v[178:181], v[202:205], v[104:107]
	v_mfma_f32_16x16x32_bf16 v[100:103], v[186:189], v[202:205], v[100:103]
	v_mfma_f32_16x16x32_bf16 v[88:91], v[178:181], v[210:213], v[88:91]
	v_mfma_f32_16x16x32_bf16 v[84:87], v[186:189], v[210:213], v[84:87]
	v_mfma_f32_16x16x32_bf16 v[72:75], v[178:181], v[218:221], v[72:75]
	v_mfma_f32_16x16x32_bf16 v[68:71], v[186:189], v[218:221], v[68:71]
	s_setprio 0
	s_barrier
	s_add_i32 s69, s57, s4
	v_lshl_add_u64 v[222:223], vcc, 0, v[134:135]
	s_mov_b32 m0, s69
	ds_read_b128 v[190:193], v156 offset:16384
	ds_read_b128 v[194:197], v156 offset:17408
	ds_read_b128 v[198:201], v156 offset:18432
	ds_read_b128 v[202:205], v156 offset:19456
	ds_read_b128 v[206:209], v156 offset:20480
	ds_read_b128 v[210:213], v156 offset:21504
	ds_read_b128 v[214:217], v156 offset:22528
	ds_read_b128 v[218:221], v156 offset:23552
	global_load_lds_dwordx4 v[222:223], off
	s_add_i32 m0, s69, 0x2000
	s_add_u32 s70, vcc_lo, 0x80000
	v_lshl_add_u64 v[224:225], vcc, 0, v[138:139]
	s_addc_u32 s71, vcc_hi, 0
	s_add_i32 s69, s58, s4
	global_load_lds_dwordx4 v[224:225], off
	v_lshl_add_u64 v[2:3], s[70:71], 0, v[134:135]
	s_mov_b32 m0, s69
	s_nop 0
	global_load_lds_dwordx4 v[2:3], off
	v_lshl_add_u64 v[2:3], s[70:71], 0, v[138:139]
	s_add_i32 m0, s69, 0x2000
	s_nop 0
	global_load_lds_dwordx4 v[2:3], off
	s_waitcnt vmcnt(6)
	s_waitcnt lgkmcnt(0)
	s_barrier
; #define PG8_STAGE(bufoff, gbase, voff) do { _Pragma("unroll") for (int _i = 0; _i < 2; ++_i) \
;         __builtin_amdgcn_global_load_lds((const unsigned*)((const char*)(gbase) + (voff)[_i]), (PG8_LAS unsigned*)(lds + (bufoff) + ldsw + _i * 8192), 16, 0, 0); } while (0)
; #define PG8_LDA(dst, b, h) do { _Pragma("unroll") for (int m = 0; m < 4; ++m) _Pragma("unroll") for (int k = 0; k < 2; ++k) dst[m][k] = *(const PG8_LAS bf16x8*)(lds + PG8_SA(b, h) + aoff + m * 2048 + k * 1024); } while (0)
; #define PG8_LDB(dst, b, h) do { _Pragma("unroll") for (int n = 0; n < 2; ++n) _Pragma("unroll") for (int k = 0; k < 2; ++k) dst[n][k] = *(const PG8_LAS bf16x8*)(lds + PG8_SB(b, h) + boff + n * 2048 + k * 1024); } while (0)
; #define PG8_MMA(ai, bj, At, Bt) do { __builtin_amdgcn_s_setprio(1); _Pragma("unroll") for (int m = 0; m < 4; ++m) _Pragma("unroll") for (int n = 0; n < 2; ++n) _Pragma("unroll") for (int k = 0; k < 2; ++k) \
;         acc[ai][bj][m][n] = __builtin_amdgcn_mfma_f32_16x16x32_bf16(Bt[n][k], At[m][k], acc[ai][bj][m][n], 0, 0, 0); __builtin_amdgcn_s_setprio(0); } while (0)
; #define PG8_WAIT_V(n) asm volatile("s_waitcnt vmcnt(" #n ")" ::: "memory")
; #define PG8_WAIT_L(n) asm volatile("s_waitcnt lgkmcnt(" #n ")" ::: "memory")
; #define PG8_BAR __builtin_amdgcn_s_barrier()
; #define PG8_SCHED __builtin_amdgcn_sched_barrier(0)
; template <class Epi, class Sched, bool ALIGN_EPI = false, bool SP2 = false>
; __device__ __forceinline__ void gemm_phase(PG8_LAS unsigned char* lds, const Gemm g, const Sched& S, const Epi& E) {
;     ...
;             PG8_WAIT_V(8); PG8_WAIT_L(0); PG8_BAR; PG8_MMA(1, 0, At, B0); PG8_MMA(1, 1, At, B1); PG8_BAR; PG8_SCHED;
;             PG8_LDB(B0, 1, 0); PG8_LDB(B1, 1, 1); PG8_SCHED; PG8_LDA(At, 1, 0); PG8_STAGE(PG8_SA(0, 1), a2 + hstepA, voffA);
;             PG8_WAIT_V(8); PG8_WAIT_L(0); PG8_BAR; PG8_MMA(0, 0, At, B0); PG8_MMA(0, 1, At, B1); PG8_BAR; PG8_SCHED;
	s_setprio 1
	s_waitcnt lgkmcnt(0)
	v_mfma_f32_16x16x32_bf16 v[64:67], v[158:161], v[190:193], v[64:67]
	v_mfma_f32_16x16x32_bf16 v[60:63], v[166:169], v[190:193], v[60:63]
	v_mfma_f32_16x16x32_bf16 v[48:51], v[158:161], v[198:201], v[48:51]
	v_mfma_f32_16x16x32_bf16 v[44:47], v[166:169], v[198:201], v[44:47]
	v_mfma_f32_16x16x32_bf16 v[32:35], v[158:161], v[206:209], v[32:35]
	v_mfma_f32_16x16x32_bf16 v[28:31], v[166:169], v[206:209], v[28:31]
	v_mfma_f32_16x16x32_bf16 v[16:19], v[158:161], v[214:217], v[16:19]
	v_mfma_f32_16x16x32_bf16 v[12:15], v[166:169], v[214:217], v[12:15]
	v_mfma_f32_16x16x32_bf16 v[64:67], v[162:165], v[194:197], v[64:67]
	v_mfma_f32_16x16x32_bf16 v[60:63], v[170:173], v[194:197], v[60:63]
	v_mfma_f32_16x16x32_bf16 v[48:51], v[162:165], v[202:205], v[48:51]
	v_mfma_f32_16x16x32_bf16 v[44:47], v[170:173], v[202:205], v[44:47]
	v_mfma_f32_16x16x32_bf16 v[32:35], v[162:165], v[210:213], v[32:35]
	v_mfma_f32_16x16x32_bf16 v[28:31], v[170:173], v[210:213], v[28:31]
	v_mfma_f32_16x16x32_bf16 v[16:19], v[162:165], v[218:221], v[16:19]
	v_mfma_f32_16x16x32_bf16 v[12:15], v[170:173], v[218:221], v[12:15]
	s_setprio 0
	s_setprio 1
	v_mfma_f32_16x16x32_bf16 v[56:59], v[174:177], v[190:193], v[56:59]
	v_mfma_f32_16x16x32_bf16 v[52:55], v[182:185], v[190:193], v[52:55]
	v_mfma_f32_16x16x32_bf16 v[40:43], v[174:177], v[198:201], v[40:43]
	v_mfma_f32_16x16x32_bf16 v[36:39], v[182:185], v[198:201], v[36:39]
	v_mfma_f32_16x16x32_bf16 v[24:27], v[174:177], v[206:209], v[24:27]
	v_mfma_f32_16x16x32_bf16 v[20:23], v[182:185], v[206:209], v[20:23]
	v_mfma_f32_16x16x32_bf16 v[8:11], v[174:177], v[214:217], v[8:11]
	v_mfma_f32_16x16x32_bf16 v[2:5], v[182:185], v[214:217], v[4:7]
	v_mfma_f32_16x16x32_bf16 v[56:59], v[178:181], v[194:197], v[56:59]
	v_mfma_f32_16x16x32_bf16 v[52:55], v[186:189], v[194:197], v[52:55]
	v_mfma_f32_16x16x32_bf16 v[40:43], v[178:181], v[202:205], v[40:43]
	v_mfma_f32_16x16x32_bf16 v[36:39], v[186:189], v[202:205], v[36:39]
	v_mfma_f32_16x16x32_bf16 v[24:27], v[178:181], v[210:213], v[24:27]
	v_mfma_f32_16x16x32_bf16 v[20:23], v[186:189], v[210:213], v[20:23]
	v_mfma_f32_16x16x32_bf16 v[8:11], v[178:181], v[218:221], v[8:11]
	v_mfma_f32_16x16x32_bf16 v[2:5], v[186:189], v[218:221], v[2:5]
	s_setprio 0
	s_barrier
	s_add_i32 s69, 0, 0x18000
	v_add_u32_e32 v1, s69, v154
	s_add_i32 s70, 0, 0x1c000
	ds_read_b128 v[158:161], v1
	ds_read_b128 v[162:165], v1 offset:1024
	ds_read_b128 v[166:169], v1 offset:2048
	ds_read_b128 v[170:173], v1 offset:3072
	v_add_u32_e32 v1, s70, v154
	ds_read_b128 v[174:177], v1
	ds_read_b128 v[178:181], v1 offset:1024
	ds_read_b128 v[182:185], v1 offset:2048
	ds_read_b128 v[186:189], v1 offset:3072
	s_mov_b64 s[100:101], s[42:43]
	s_add_u32 s42, s42, 0x80000
	s_addc_u32 s43, s43, 0
	s_mov_b32 m0, s7
	v_lshl_add_u64 v[6:7], s[42:43], 0, v[132:133]
	ds_read_b128 v[190:193], v156 offset:32768
	ds_read_b128 v[194:197], v156 offset:33792
	ds_read_b128 v[198:201], v156 offset:34816
	ds_read_b128 v[202:205], v156 offset:35840
	ds_read_b128 v[206:209], v156 offset:36864
	ds_read_b128 v[210:213], v156 offset:37888
	ds_read_b128 v[214:217], v156 offset:38912
	ds_read_b128 v[218:221], v156 offset:39936
	s_mov_b32 m0, s5
	s_nop 0
	global_load_lds_dwordx4 v132, s[100:101]
	s_mov_b32 m0, s6
	s_nop 0
	global_load_lds_dwordx4 v136, s[100:101]
	s_mov_b32 m0, s7
	s_nop 0
	global_load_lds_dwordx4 v[6:7], off
	v_lshl_add_u64 v[6:7], s[42:43], 0, v[136:137]
	s_mov_b32 m0, s33
	s_nop 0
	global_load_lds_dwordx4 v[6:7], off
	s_waitcnt vmcnt(8)
	s_waitcnt lgkmcnt(0)
	s_barrier
; #define PG8_STAGE(bufoff, gbase, voff) do { _Pragma("unroll") for (int _i = 0; _i < 2; ++_i) \
;         __builtin_amdgcn_global_load_lds((const unsigned*)((const char*)(gbase) + (voff)[_i]), (PG8_LAS unsigned*)(lds + (bufoff) + ldsw + _i * 8192), 16, 0, 0); } while (0)
; #define PG8_LDA(dst, b, h) do { _Pragma("unroll") for (int m = 0; m < 4; ++m) _Pragma("unroll") for (int k = 0; k < 2; ++k) dst[m][k] = *(const PG8_LAS bf16x8*)(lds + PG8_SA(b, h) + aoff + m * 2048 + k * 1024); } while (0)
; #define PG8_MMA(ai, bj, At, Bt) do { __builtin_amdgcn_s_setprio(1); _Pragma("unroll") for (int m = 0; m < 4; ++m) _Pragma("unroll") for (int n = 0; n < 2; ++n) _Pragma("unroll") for (int k = 0; k < 2; ++k) \
;         acc[ai][bj][m][n] = __builtin_amdgcn_mfma_f32_16x16x32_bf16(Bt[n][k], At[m][k], acc[ai][bj][m][n], 0, 0, 0); __builtin_amdgcn_s_setprio(0); } while (0)
; #define PG8_WAIT_V(n) asm volatile("s_waitcnt vmcnt(" #n ")" ::: "memory")
; #define PG8_WAIT_L(n) asm volatile("s_waitcnt lgkmcnt(" #n ")" ::: "memory")
; #define PG8_BAR __builtin_amdgcn_s_barrier()
; #define PG8_SCHED __builtin_amdgcn_sched_barrier(0)
; template <class Epi, class Sched, bool ALIGN_EPI = false, bool SP2 = false>
; __device__ __forceinline__ void gemm_phase(PG8_LAS unsigned char* lds, const Gemm g, const Sched& S, const Epi& E) {
;     ...
;             PG8_WAIT_V(8); PG8_WAIT_L(0); PG8_BAR; PG8_MMA(0, 0, At, B0); PG8_MMA(0, 1, At, B1); PG8_BAR; PG8_SCHED;
;             PG8_LDA(At, 1, 1); PG8_STAGE(PG8_SB(1, 0), b3, voffB); PG8_STAGE(PG8_SB(1, 1), b3 + hstepB, voffB); PG8_STAGE(PG8_SA(1, 0), a3, voffA);
;             PG8_WAIT_V(8); PG8_WAIT_L(0); PG8_BAR; PG8_MMA(1, 0, At, B0); PG8_MMA(1, 1, At, B1); PG8_BAR; PG8_SCHED;
	s_setprio 1
	s_waitcnt lgkmcnt(0)
	v_mfma_f32_16x16x32_bf16 v[128:131], v[158:161], v[190:193], v[128:131]
	v_mfma_f32_16x16x32_bf16 v[124:127], v[166:169], v[190:193], v[124:127]
	v_mfma_f32_16x16x32_bf16 v[112:115], v[158:161], v[198:201], v[112:115]
	v_mfma_f32_16x16x32_bf16 v[108:111], v[166:169], v[198:201], v[108:111]
	v_mfma_f32_16x16x32_bf16 v[96:99], v[158:161], v[206:209], v[96:99]
	v_mfma_f32_16x16x32_bf16 v[92:95], v[166:169], v[206:209], v[92:95]
	v_mfma_f32_16x16x32_bf16 v[80:83], v[158:161], v[214:217], v[80:83]
	v_mfma_f32_16x16x32_bf16 v[76:79], v[166:169], v[214:217], v[76:79]
	v_mfma_f32_16x16x32_bf16 v[128:131], v[162:165], v[194:197], v[128:131]
	v_mfma_f32_16x16x32_bf16 v[124:127], v[170:173], v[194:197], v[124:127]
	v_mfma_f32_16x16x32_bf16 v[112:115], v[162:165], v[202:205], v[112:115]
	v_mfma_f32_16x16x32_bf16 v[108:111], v[170:173], v[202:205], v[108:111]
	v_mfma_f32_16x16x32_bf16 v[96:99], v[162:165], v[210:213], v[96:99]
	v_mfma_f32_16x16x32_bf16 v[92:95], v[170:173], v[210:213], v[92:95]
	v_mfma_f32_16x16x32_bf16 v[80:83], v[162:165], v[218:221], v[80:83]
	v_mfma_f32_16x16x32_bf16 v[76:79], v[170:173], v[218:221], v[76:79]
	s_setprio 0
	s_setprio 1
	v_mfma_f32_16x16x32_bf16 v[120:123], v[174:177], v[190:193], v[120:123]
	v_mfma_f32_16x16x32_bf16 v[116:119], v[182:185], v[190:193], v[116:119]
	v_mfma_f32_16x16x32_bf16 v[104:107], v[174:177], v[198:201], v[104:107]
	v_mfma_f32_16x16x32_bf16 v[100:103], v[182:185], v[198:201], v[100:103]
	v_mfma_f32_16x16x32_bf16 v[88:91], v[174:177], v[206:209], v[88:91]
	v_mfma_f32_16x16x32_bf16 v[84:87], v[182:185], v[206:209], v[84:87]
	v_mfma_f32_16x16x32_bf16 v[72:75], v[174:177], v[214:217], v[72:75]
	v_mfma_f32_16x16x32_bf16 v[68:71], v[182:185], v[214:217], v[68:71]
	v_mfma_f32_16x16x32_bf16 v[120:123], v[178:181], v[194:197], v[120:123]
	v_mfma_f32_16x16x32_bf16 v[116:119], v[186:189], v[194:197], v[116:119]
	v_mfma_f32_16x16x32_bf16 v[104:107], v[178:181], v[202:205], v[104:107]
	v_mfma_f32_16x16x32_bf16 v[100:103], v[186:189], v[202:205], v[100:103]
	v_mfma_f32_16x16x32_bf16 v[88:91], v[178:181], v[210:213], v[88:91]
	v_mfma_f32_16x16x32_bf16 v[84:87], v[186:189], v[210:213], v[84:87]
	v_mfma_f32_16x16x32_bf16 v[72:75], v[178:181], v[218:221], v[72:75]
	v_mfma_f32_16x16x32_bf16 v[68:71], v[186:189], v[218:221], v[68:71]
	s_setprio 0
	s_barrier
	s_add_i32 s42, s69, s4
	v_lshl_add_u64 v[6:7], v[222:223], 0, s[30:31]
	s_mov_b32 m0, s42
	ds_read_b128 v[190:193], v156 offset:49152
	ds_read_b128 v[194:197], v156 offset:50176
	ds_read_b128 v[198:201], v156 offset:51200
	ds_read_b128 v[202:205], v156 offset:52224
	ds_read_b128 v[206:209], v156 offset:53248
	ds_read_b128 v[210:213], v156 offset:54272
	ds_read_b128 v[214:217], v156 offset:55296
	ds_read_b128 v[218:221], v156 offset:56320
	global_load_lds_dwordx4 v[6:7], off
	s_add_i32 m0, s42, 0x2000
	s_add_u32 s42, vcc_lo, 0x80080
	v_lshl_add_u64 v[6:7], v[224:225], 0, s[30:31]
	s_addc_u32 s43, vcc_hi, 0
	s_add_i32 s69, s70, s4
	global_load_lds_dwordx4 v[6:7], off
	v_lshl_add_u64 v[6:7], s[42:43], 0, v[134:135]
	s_mov_b32 m0, s69
	s_nop 0
	global_load_lds_dwordx4 v[6:7], off
	v_lshl_add_u64 v[6:7], s[42:43], 0, v[138:139]
	s_add_i32 m0, s69, 0x2000
	s_nop 0
	global_load_lds_dwordx4 v[6:7], off
	s_waitcnt vmcnt(6)
	s_waitcnt lgkmcnt(0)
	s_barrier
	s_setprio 1
	s_waitcnt lgkmcnt(0)
	v_mfma_f32_16x16x32_bf16 v[64:67], v[158:161], v[190:193], v[64:67]
	v_mfma_f32_16x16x32_bf16 v[60:63], v[166:169], v[190:193], v[60:63]
	v_mfma_f32_16x16x32_bf16 v[48:51], v[158:161], v[198:201], v[48:51]
	v_mfma_f32_16x16x32_bf16 v[44:47], v[166:169], v[198:201], v[44:47]
	v_mfma_f32_16x16x32_bf16 v[32:35], v[158:161], v[206:209], v[32:35]
	v_mfma_f32_16x16x32_bf16 v[28:31], v[166:169], v[206:209], v[28:31]
	v_mfma_f32_16x16x32_bf16 v[16:19], v[158:161], v[214:217], v[16:19]
	v_mfma_f32_16x16x32_bf16 v[12:15], v[166:169], v[214:217], v[12:15]
	v_mfma_f32_16x16x32_bf16 v[64:67], v[162:165], v[194:197], v[64:67]
	v_mfma_f32_16x16x32_bf16 v[60:63], v[170:173], v[194:197], v[60:63]
	v_mfma_f32_16x16x32_bf16 v[48:51], v[162:165], v[202:205], v[48:51]
	v_mfma_f32_16x16x32_bf16 v[44:47], v[170:173], v[202:205], v[44:47]
	v_mfma_f32_16x16x32_bf16 v[32:35], v[162:165], v[210:213], v[32:35]
	v_mfma_f32_16x16x32_bf16 v[28:31], v[170:173], v[210:213], v[28:31]
	v_mfma_f32_16x16x32_bf16 v[16:19], v[162:165], v[218:221], v[16:19]
	v_mfma_f32_16x16x32_bf16 v[12:15], v[170:173], v[218:221], v[12:15]
	s_setprio 0
	s_setprio 1
	v_mfma_f32_16x16x32_bf16 v[56:59], v[174:177], v[190:193], v[56:59]
	v_mfma_f32_16x16x32_bf16 v[52:55], v[182:185], v[190:193], v[52:55]
	v_mfma_f32_16x16x32_bf16 v[40:43], v[174:177], v[198:201], v[40:43]
	v_mfma_f32_16x16x32_bf16 v[36:39], v[182:185], v[198:201], v[36:39]
	v_mfma_f32_16x16x32_bf16 v[24:27], v[174:177], v[206:209], v[24:27]
	v_mfma_f32_16x16x32_bf16 v[20:23], v[182:185], v[206:209], v[20:23]
	v_mfma_f32_16x16x32_bf16 v[6:9], v[174:177], v[214:217], v[8:11]
	v_mfma_f32_16x16x32_bf16 v[2:5], v[182:185], v[214:217], v[2:5]
	v_mfma_f32_16x16x32_bf16 v[56:59], v[178:181], v[194:197], v[56:59]
	v_mfma_f32_16x16x32_bf16 v[52:55], v[186:189], v[194:197], v[52:55]
	v_mfma_f32_16x16x32_bf16 v[40:43], v[178:181], v[202:205], v[40:43]
	v_mfma_f32_16x16x32_bf16 v[36:39], v[186:189], v[202:205], v[36:39]
	v_mfma_f32_16x16x32_bf16 v[24:27], v[178:181], v[210:213], v[24:27]
	v_mfma_f32_16x16x32_bf16 v[20:23], v[186:189], v[210:213], v[20:23]
	v_mfma_f32_16x16x32_bf16 v[8:11], v[178:181], v[218:221], v[6:9]
	v_mfma_f32_16x16x32_bf16 v[4:7], v[186:189], v[218:221], v[2:5]
	s_setprio 0
	s_barrier
	s_add_i32 s68, s68, 2
	s_add_u32 s18, s18, 0x100
	s_addc_u32 s19, s19, 0
	s_cmp_gt_u32 s68, 29
	s_cbranch_scc1 .LBB0_1220

; #define PG8_STAGE(bufoff, gbase, voff) do { _Pragma("unroll") for (int _i = 0; _i < 2; ++_i) \
;         __builtin_amdgcn_global_load_lds((const unsigned*)((const char*)(gbase) + (voff)[_i]), (PG8_LAS unsigned*)(lds + (bufoff) + ldsw + _i * 8192), 16, 0, 0); } while (0)
; #define PG8_LDA(dst, b, h) do { _Pragma("unroll") for (int m = 0; m < 4; ++m) _Pragma("unroll") for (int k = 0; k < 2; ++k) dst[m][k] = *(const PG8_LAS bf16x8*)(lds + PG8_SA(b, h) + aoff + m * 2048 + k * 1024); } while (0)
; #define PG8_LDB(dst, b, h) do { _Pragma("unroll") for (int n = 0; n < 2; ++n) _Pragma("unroll") for (int k = 0; k < 2; ++k) dst[n][k] = *(const PG8_LAS bf16x8*)(lds + PG8_SB(b, h) + boff + n * 2048 + k * 1024); } while (0)
; #define PG8_WAIT_V(n) asm volatile("s_waitcnt vmcnt(" #n ")" ::: "memory")
; #define PG8_WAIT_L(n) asm volatile("s_waitcnt lgkmcnt(" #n ")" ::: "memory")
; #define PG8_BAR __builtin_amdgcn_s_barrier()
; #define PG8_SCHED __builtin_amdgcn_sched_barrier(0)
; template <class Epi, class Sched, bool ALIGN_EPI = false, bool SP2 = false>
; __device__ __forceinline__ void gemm_phase(PG8_LAS unsigned char* lds, const Gemm g, const Sched& S, const Epi& E) {
;     ...
;         const char* nA = has_next ? (const char*)g.A + (size_t)nxt.pm * tstepA : cA; const char* nB = has_next ? (const char*)g.Bt + (size_t)nxt.pn * tstepB : cB;
;         for (int t = 0; t < nt; t += 2) {
;             const bool last = (t == nt - 2);
;             if constexpr (Epi::HAS_MID) { if (t == E.mid_t) E.mid(acc, cur, wr, wc, fr, fq); }
;             const char* a1 = cA + (size_t)(t + 1) * kstep;
;             const char* a2 = last ? nA : cA + (size_t)(t + 2) * kstep; const char* b2 = last ? nB : cB + (size_t)(t + 2) * kstep;
;             const char* a3 = a2 + kstep; const char* b3 = b2 + kstep;
;             if (last && has_next) S.a_ready(nxt);
;             if constexpr (SP2) {
;             PG8_LDB(B0, 0, 0); PG8_LDB(B1, 0, 1); PG8_SCHED; PG8_LDA(At, 0, 0); PG8_STAGE(PG8_SA(1, 1), a1 + hstepA, voffA);
;             PG8_WAIT_V(8); PG8_WAIT_L(0); PG8_BAR; PG8_MMA(0, 0, At, B0); PG8_MMA(0, 1, At, B1); PG8_BAR; PG8_SCHED;
;             PG8_LDA(At, 0, 1); PG8_STAGE(PG8_SB(0, 0), b2, voffB); PG8_STAGE(PG8_SB(0, 1), b2 + hstepB, voffB); PG8_STAGE(PG8_SA(0, 0), a2, voffA);
;             PG8_WAIT_V(8); PG8_WAIT_L(0); PG8_BAR; PG8_MMA(1, 0, At, B0); PG8_MMA(1, 1, At, B1); PG8_BAR; PG8_SCHED;
.LBB0_1309:
	ds_read_b128 v[128:131], v161
	ds_read_b128 v[132:135], v161 offset:1024
	ds_read_b128 v[148:151], v161 offset:2048
	ds_read_b128 v[152:155], v161 offset:3072
	ds_read_b128 v[166:169], v162
	ds_read_b128 v[170:173], v162 offset:1024
	ds_read_b128 v[174:177], v162 offset:2048
	ds_read_b128 v[178:181], v162 offset:3072
	s_add_u32 s16, s12, 0xfff80080
	s_addc_u32 s17, s13, -1
	s_cmp_eq_u32 s65, 28
	s_cselect_b32 s19, s39, s17
	s_cselect_b32 s18, s59, s16
	s_cselect_b32 s17, s37, s63
	s_cselect_b32 s16, s61, s62
	s_add_i32 m0, s5, 0xc000
	ds_read_b128 v[182:185], v163
	ds_read_b128 v[186:189], v163 offset:1024
	ds_read_b128 v[190:193], v163 offset:2048
	ds_read_b128 v[194:197], v163 offset:3072
	ds_read_b128 v[198:201], v163 offset:4096
	ds_read_b128 v[202:205], v163 offset:5120
	ds_read_b128 v[206:209], v163 offset:6144
	ds_read_b128 v[210:213], v163 offset:7168
	s_add_u32 s98, s12, 0xfff80000
	s_addc_u32 s99, s13, -1
	s_mov_b32 m0, s33
	s_nop 0
	global_load_lds_dwordx4 v136, s[98:99]
	s_mov_b32 m0, s34
	s_nop 0
	global_load_lds_dwordx4 v140, s[98:99]
	s_add_i32 m0, s5, 0xc000
	s_nop 0
	global_load_lds_dwordx4 v144, s[12:13]
	s_add_i32 m0, s5, 0xe000
	s_nop 0
	global_load_lds_dwordx4 v146, s[12:13]
	s_waitcnt vmcnt(8)
	s_waitcnt lgkmcnt(0)
	s_barrier
	s_setprio 1
	s_waitcnt lgkmcnt(0)
	v_mfma_f32_16x16x32_bf16 v[124:127], v[128:131], v[182:185], v[124:127]
	v_mfma_f32_16x16x32_bf16 v[120:123], v[148:151], v[182:185], v[120:123]
	v_mfma_f32_16x16x32_bf16 v[108:111], v[128:131], v[190:193], v[108:111]
	v_mfma_f32_16x16x32_bf16 v[104:107], v[148:151], v[190:193], v[104:107]
	v_mfma_f32_16x16x32_bf16 v[92:95], v[128:131], v[198:201], v[92:95]
	v_mfma_f32_16x16x32_bf16 v[88:91], v[148:151], v[198:201], v[88:91]
	v_mfma_f32_16x16x32_bf16 v[76:79], v[128:131], v[206:209], v[76:79]
	v_mfma_f32_16x16x32_bf16 v[72:75], v[148:151], v[206:209], v[72:75]
	v_mfma_f32_16x16x32_bf16 v[124:127], v[132:135], v[186:189], v[124:127]
	v_mfma_f32_16x16x32_bf16 v[120:123], v[152:155], v[186:189], v[120:123]
	v_mfma_f32_16x16x32_bf16 v[108:111], v[132:135], v[194:197], v[108:111]
	v_mfma_f32_16x16x32_bf16 v[104:107], v[152:155], v[194:197], v[104:107]
	v_mfma_f32_16x16x32_bf16 v[92:95], v[132:135], v[202:205], v[92:95]
	v_mfma_f32_16x16x32_bf16 v[88:91], v[152:155], v[202:205], v[88:91]
	v_mfma_f32_16x16x32_bf16 v[76:79], v[132:135], v[210:213], v[76:79]
	v_mfma_f32_16x16x32_bf16 v[72:75], v[152:155], v[210:213], v[72:75]
	s_setprio 0
	s_setprio 1
	v_mfma_f32_16x16x32_bf16 v[116:119], v[166:169], v[182:185], v[116:119]
	v_mfma_f32_16x16x32_bf16 v[112:115], v[174:177], v[182:185], v[112:115]
	v_mfma_f32_16x16x32_bf16 v[100:103], v[166:169], v[190:193], v[100:103]
	v_mfma_f32_16x16x32_bf16 v[96:99], v[174:177], v[190:193], v[96:99]
	v_mfma_f32_16x16x32_bf16 v[84:87], v[166:169], v[198:201], v[84:87]
	v_mfma_f32_16x16x32_bf16 v[80:83], v[174:177], v[198:201], v[80:83]
	v_mfma_f32_16x16x32_bf16 v[68:71], v[166:169], v[206:209], v[68:71]
	v_mfma_f32_16x16x32_bf16 v[64:67], v[174:177], v[206:209], v[64:67]
	v_mfma_f32_16x16x32_bf16 v[116:119], v[170:173], v[186:189], v[116:119]
	v_mfma_f32_16x16x32_bf16 v[112:115], v[178:181], v[186:189], v[112:115]
	v_mfma_f32_16x16x32_bf16 v[100:103], v[170:173], v[194:197], v[100:103]
	v_mfma_f32_16x16x32_bf16 v[96:99], v[178:181], v[194:197], v[96:99]
	v_mfma_f32_16x16x32_bf16 v[84:87], v[170:173], v[202:205], v[84:87]
	v_mfma_f32_16x16x32_bf16 v[80:83], v[178:181], v[202:205], v[80:83]
	v_mfma_f32_16x16x32_bf16 v[68:71], v[170:173], v[210:213], v[68:71]
	v_mfma_f32_16x16x32_bf16 v[64:67], v[178:181], v[210:213], v[64:67]
	s_setprio 0
	s_barrier
	s_add_i32 s66, s56, s4
	s_mov_b32 m0, s66
	ds_read_b128 v[182:185], v163 offset:16384
	ds_read_b128 v[186:189], v163 offset:17408
	ds_read_b128 v[190:193], v163 offset:18432
	ds_read_b128 v[194:197], v163 offset:19456
	ds_read_b128 v[198:201], v163 offset:20480
	ds_read_b128 v[202:205], v163 offset:21504
	ds_read_b128 v[206:209], v163 offset:22528
	ds_read_b128 v[210:213], v163 offset:23552
	global_load_lds_dwordx4 v138, s[16:17]
	s_add_i32 m0, s66, 0x2000
	s_add_u32 s66, s16, 0x80000
	s_addc_u32 s67, s17, 0
	s_add_i32 s68, s57, s4
	global_load_lds_dwordx4 v142, s[16:17]
	s_mov_b32 m0, s68
	s_nop 0
	global_load_lds_dwordx4 v138, s[66:67]
	s_add_i32 m0, s68, 0x2000
	s_nop 0
	global_load_lds_dwordx4 v142, s[66:67]
	s_waitcnt vmcnt(6)
	s_waitcnt lgkmcnt(0)
	s_barrier
	s_setprio 1
	s_waitcnt lgkmcnt(0)
	v_mfma_f32_16x16x32_bf16 v[60:63], v[128:131], v[182:185], v[60:63]
	v_mfma_f32_16x16x32_bf16 v[56:59], v[148:151], v[182:185], v[56:59]
	v_mfma_f32_16x16x32_bf16 v[44:47], v[128:131], v[190:193], v[44:47]
	v_mfma_f32_16x16x32_bf16 v[40:43], v[148:151], v[190:193], v[40:43]
	v_mfma_f32_16x16x32_bf16 v[28:31], v[128:131], v[198:201], v[28:31]
	v_mfma_f32_16x16x32_bf16 v[24:27], v[148:151], v[198:201], v[24:27]
	v_mfma_f32_16x16x32_bf16 v[12:15], v[128:131], v[206:209], v[12:15]
	v_mfma_f32_16x16x32_bf16 v[8:11], v[148:151], v[206:209], v[8:11]
	v_mfma_f32_16x16x32_bf16 v[60:63], v[132:135], v[186:189], v[60:63]
	v_mfma_f32_16x16x32_bf16 v[56:59], v[152:155], v[186:189], v[56:59]
	v_mfma_f32_16x16x32_bf16 v[44:47], v[132:135], v[194:197], v[44:47]
	v_mfma_f32_16x16x32_bf16 v[40:43], v[152:155], v[194:197], v[40:43]
	v_mfma_f32_16x16x32_bf16 v[28:31], v[132:135], v[202:205], v[28:31]
	v_mfma_f32_16x16x32_bf16 v[24:27], v[152:155], v[202:205], v[24:27]
	v_mfma_f32_16x16x32_bf16 v[12:15], v[132:135], v[210:213], v[12:15]
	v_mfma_f32_16x16x32_bf16 v[8:11], v[152:155], v[210:213], v[8:11]
	s_setprio 0
	s_setprio 1
	v_mfma_f32_16x16x32_bf16 v[52:55], v[166:169], v[182:185], v[52:55]
	v_mfma_f32_16x16x32_bf16 v[48:51], v[174:177], v[182:185], v[48:51]
	v_mfma_f32_16x16x32_bf16 v[36:39], v[166:169], v[190:193], v[36:39]
	v_mfma_f32_16x16x32_bf16 v[32:35], v[174:177], v[190:193], v[32:35]
	v_mfma_f32_16x16x32_bf16 v[20:23], v[166:169], v[198:201], v[20:23]
	v_mfma_f32_16x16x32_bf16 v[16:19], v[174:177], v[198:201], v[16:19]
	v_mfma_f32_16x16x32_bf16 v[4:7], v[166:169], v[206:209], v[4:7]
	v_mfma_f32_16x16x32_bf16 v[0:3], v[174:177], v[206:209], v[0:3]
	v_mfma_f32_16x16x32_bf16 v[52:55], v[170:173], v[186:189], v[52:55]
	v_mfma_f32_16x16x32_bf16 v[48:51], v[178:181], v[186:189], v[48:51]
	v_mfma_f32_16x16x32_bf16 v[36:39], v[170:173], v[194:197], v[36:39]
	v_mfma_f32_16x16x32_bf16 v[32:35], v[178:181], v[194:197], v[32:35]
	v_mfma_f32_16x16x32_bf16 v[20:23], v[170:173], v[202:205], v[20:23]
	v_mfma_f32_16x16x32_bf16 v[16:19], v[178:181], v[202:205], v[16:19]
	v_mfma_f32_16x16x32_bf16 v[4:7], v[170:173], v[210:213], v[4:7]
	v_mfma_f32_16x16x32_bf16 v[0:3], v[178:181], v[210:213], v[0:3]
	s_setprio 0
	s_barrier
; #define PG8_STAGE(bufoff, gbase, voff) do { _Pragma("unroll") for (int _i = 0; _i < 2; ++_i) \
;         __builtin_amdgcn_global_load_lds((const unsigned*)((const char*)(gbase) + (voff)[_i]), (PG8_LAS unsigned*)(lds + (bufoff) + ldsw + _i * 8192), 16, 0, 0); } while (0)
; #define PG8_LDA(dst, b, h) do { _Pragma("unroll") for (int m = 0; m < 4; ++m) _Pragma("unroll") for (int k = 0; k < 2; ++k) dst[m][k] = *(const PG8_LAS bf16x8*)(lds + PG8_SA(b, h) + aoff + m * 2048 + k * 1024); } while (0)
; #define PG8_LDB(dst, b, h) do { _Pragma("unroll") for (int n = 0; n < 2; ++n) _Pragma("unroll") for (int k = 0; k < 2; ++k) dst[n][k] = *(const PG8_LAS bf16x8*)(lds + PG8_SB(b, h) + boff + n * 2048 + k * 1024); } while (0)
; #define PG8_MMA(ai, bj, At, Bt) do { __builtin_amdgcn_s_setprio(1); _Pragma("unroll") for (int m = 0; m < 4; ++m) _Pragma("unroll") for (int n = 0; n < 2; ++n) _Pragma("unroll") for (int k = 0; k < 2; ++k) \
;         acc[ai][bj][m][n] = __builtin_amdgcn_mfma_f32_16x16x32_bf16(Bt[n][k], At[m][k], acc[ai][bj][m][n], 0, 0, 0); __builtin_amdgcn_s_setprio(0); } while (0)
; #define PG8_WAIT_V(n) asm volatile("s_waitcnt vmcnt(" #n ")" ::: "memory")
; #define PG8_WAIT_L(n) asm volatile("s_waitcnt lgkmcnt(" #n ")" ::: "memory")
; #define PG8_BAR __builtin_amdgcn_s_barrier()
; #define PG8_SCHED __builtin_amdgcn_sched_barrier(0)
; template <class Epi, class Sched, bool ALIGN_EPI = false, bool SP2 = false>
; __device__ __forceinline__ void gemm_phase(PG8_LAS unsigned char* lds, const Gemm g, const Sched& S, const Epi& E) {
;     ...
;             PG8_LDB(B0, 1, 0); PG8_LDB(B1, 1, 1); PG8_SCHED; PG8_LDA(At, 1, 0); PG8_STAGE(PG8_SA(0, 1), a2 + hstepA, voffA);
;             PG8_WAIT_V(8); PG8_WAIT_L(0); PG8_BAR; PG8_MMA(0, 0, At, B0); PG8_MMA(0, 1, At, B1); PG8_BAR; PG8_SCHED;
;             PG8_LDA(At, 1, 1); PG8_STAGE(PG8_SB(1, 0), b3, voffB); PG8_STAGE(PG8_SB(1, 1), b3 + hstepB, voffB); PG8_STAGE(PG8_SA(1, 0), a3, voffA);
;             PG8_WAIT_V(8); PG8_WAIT_L(0); PG8_BAR; PG8_MMA(1, 0, At, B0); PG8_MMA(1, 1, At, B1); PG8_BAR; PG8_SCHED;
;     ...
;         if constexpr (ALIGN_EPI) { if (wr == 0) PG8_BAR; }
	s_add_i32 s66, 0, 0x18000
	s_add_i32 s67, 0, 0x1c000
	v_add_u32_e32 v152, s66, v160
	v_add_u32_e32 v165, s67, v160
	ds_read_b128 v[128:131], v152
	ds_read_b128 v[132:135], v152 offset:1024
	ds_read_b128 v[148:151], v152 offset:2048
	ds_read_b128 v[152:155], v152 offset:3072
	ds_read_b128 v[166:169], v165
	ds_read_b128 v[170:173], v165 offset:1024
	ds_read_b128 v[174:177], v165 offset:2048
	ds_read_b128 v[178:181], v165 offset:3072
	s_mov_b64 s[100:101], s[18:19]
	s_add_u32 s18, s18, 0x80000
	s_addc_u32 s19, s19, 0
	s_mov_b32 m0, s7
	ds_read_b128 v[182:185], v163 offset:32768
	ds_read_b128 v[186:189], v163 offset:33792
	ds_read_b128 v[190:193], v163 offset:34816
	ds_read_b128 v[194:197], v163 offset:35840
	ds_read_b128 v[198:201], v163 offset:36864
	ds_read_b128 v[202:205], v163 offset:37888
	ds_read_b128 v[206:209], v163 offset:38912
	ds_read_b128 v[210:213], v163 offset:39936
	s_mov_b32 m0, s5
	s_nop 0
	global_load_lds_dwordx4 v136, s[100:101]
	s_mov_b32 m0, s6
	s_nop 0
	global_load_lds_dwordx4 v140, s[100:101]
	s_mov_b32 m0, s7
	s_nop 0
	global_load_lds_dwordx4 v136, s[18:19]
	s_mov_b32 m0, s20
	s_nop 0
	global_load_lds_dwordx4 v140, s[18:19]
	s_waitcnt vmcnt(8)
	s_waitcnt lgkmcnt(0)
	s_barrier
	s_setprio 1
	s_waitcnt lgkmcnt(0)
	v_mfma_f32_16x16x32_bf16 v[124:127], v[128:131], v[182:185], v[124:127]
	v_mfma_f32_16x16x32_bf16 v[120:123], v[148:151], v[182:185], v[120:123]
	v_mfma_f32_16x16x32_bf16 v[108:111], v[128:131], v[190:193], v[108:111]
	v_mfma_f32_16x16x32_bf16 v[104:107], v[148:151], v[190:193], v[104:107]
	v_mfma_f32_16x16x32_bf16 v[92:95], v[128:131], v[198:201], v[92:95]
	v_mfma_f32_16x16x32_bf16 v[88:91], v[148:151], v[198:201], v[88:91]
	v_mfma_f32_16x16x32_bf16 v[76:79], v[128:131], v[206:209], v[76:79]
	v_mfma_f32_16x16x32_bf16 v[72:75], v[148:151], v[206:209], v[72:75]
	v_mfma_f32_16x16x32_bf16 v[124:127], v[132:135], v[186:189], v[124:127]
	v_mfma_f32_16x16x32_bf16 v[120:123], v[152:155], v[186:189], v[120:123]
	v_mfma_f32_16x16x32_bf16 v[108:111], v[132:135], v[194:197], v[108:111]
	v_mfma_f32_16x16x32_bf16 v[104:107], v[152:155], v[194:197], v[104:107]
	v_mfma_f32_16x16x32_bf16 v[92:95], v[132:135], v[202:205], v[92:95]
	v_mfma_f32_16x16x32_bf16 v[88:91], v[152:155], v[202:205], v[88:91]
	v_mfma_f32_16x16x32_bf16 v[76:79], v[132:135], v[210:213], v[76:79]
	v_mfma_f32_16x16x32_bf16 v[72:75], v[152:155], v[210:213], v[72:75]
	s_setprio 0
	s_setprio 1
	v_mfma_f32_16x16x32_bf16 v[116:119], v[166:169], v[182:185], v[116:119]
	v_mfma_f32_16x16x32_bf16 v[112:115], v[174:177], v[182:185], v[112:115]
	v_mfma_f32_16x16x32_bf16 v[100:103], v[166:169], v[190:193], v[100:103]
	v_mfma_f32_16x16x32_bf16 v[96:99], v[174:177], v[190:193], v[96:99]
	v_mfma_f32_16x16x32_bf16 v[84:87], v[166:169], v[198:201], v[84:87]
	v_mfma_f32_16x16x32_bf16 v[80:83], v[174:177], v[198:201], v[80:83]
	v_mfma_f32_16x16x32_bf16 v[68:71], v[166:169], v[206:209], v[68:71]
	v_mfma_f32_16x16x32_bf16 v[64:67], v[174:177], v[206:209], v[64:67]
	v_mfma_f32_16x16x32_bf16 v[116:119], v[170:173], v[186:189], v[116:119]
	v_mfma_f32_16x16x32_bf16 v[112:115], v[178:181], v[186:189], v[112:115]
	v_mfma_f32_16x16x32_bf16 v[100:103], v[170:173], v[194:197], v[100:103]
	v_mfma_f32_16x16x32_bf16 v[96:99], v[178:181], v[194:197], v[96:99]
	v_mfma_f32_16x16x32_bf16 v[84:87], v[170:173], v[202:205], v[84:87]
	v_mfma_f32_16x16x32_bf16 v[80:83], v[178:181], v[202:205], v[80:83]
	v_mfma_f32_16x16x32_bf16 v[68:71], v[170:173], v[210:213], v[68:71]
	v_mfma_f32_16x16x32_bf16 v[64:67], v[178:181], v[210:213], v[64:67]
	s_setprio 0
	s_barrier
	s_add_i32 s18, s66, s4
	s_add_u32 s98, s16, 0x80
	s_addc_u32 s99, s17, 0
	s_mov_b32 m0, s18
	ds_read_b128 v[182:185], v163 offset:49152
	ds_read_b128 v[186:189], v163 offset:50176
	ds_read_b128 v[190:193], v163 offset:51200
	ds_read_b128 v[194:197], v163 offset:52224
	ds_read_b128 v[198:201], v163 offset:53248
	ds_read_b128 v[202:205], v163 offset:54272
	ds_read_b128 v[206:209], v163 offset:55296
	ds_read_b128 v[210:213], v163 offset:56320
	global_load_lds_dwordx4 v138, s[98:99]
	s_add_i32 m0, s18, 0x2000
	s_add_u32 s16, s16, 0x80080
	s_addc_u32 s17, s17, 0
	s_add_i32 s18, s67, s4
	global_load_lds_dwordx4 v142, s[98:99]
	s_mov_b32 m0, s18
	s_nop 0
	global_load_lds_dwordx4 v138, s[16:17]
	s_add_i32 m0, s18, 0x2000
	s_nop 0
	global_load_lds_dwordx4 v142, s[16:17]
	s_waitcnt vmcnt(6)
	s_waitcnt lgkmcnt(0)
	s_barrier
	s_setprio 1
	s_waitcnt lgkmcnt(0)
	v_mfma_f32_16x16x32_bf16 v[60:63], v[128:131], v[182:185], v[60:63]
	v_mfma_f32_16x16x32_bf16 v[56:59], v[148:151], v[182:185], v[56:59]
	v_mfma_f32_16x16x32_bf16 v[44:47], v[128:131], v[190:193], v[44:47]
	v_mfma_f32_16x16x32_bf16 v[40:43], v[148:151], v[190:193], v[40:43]
	v_mfma_f32_16x16x32_bf16 v[28:31], v[128:131], v[198:201], v[28:31]
	v_mfma_f32_16x16x32_bf16 v[24:27], v[148:151], v[198:201], v[24:27]
	v_mfma_f32_16x16x32_bf16 v[12:15], v[128:131], v[206:209], v[12:15]
	v_mfma_f32_16x16x32_bf16 v[8:11], v[148:151], v[206:209], v[8:11]
	v_mfma_f32_16x16x32_bf16 v[60:63], v[132:135], v[186:189], v[60:63]
	v_mfma_f32_16x16x32_bf16 v[56:59], v[152:155], v[186:189], v[56:59]
	v_mfma_f32_16x16x32_bf16 v[44:47], v[132:135], v[194:197], v[44:47]
	v_mfma_f32_16x16x32_bf16 v[40:43], v[152:155], v[194:197], v[40:43]
	v_mfma_f32_16x16x32_bf16 v[28:31], v[132:135], v[202:205], v[28:31]
	v_mfma_f32_16x16x32_bf16 v[24:27], v[152:155], v[202:205], v[24:27]
	v_mfma_f32_16x16x32_bf16 v[12:15], v[132:135], v[210:213], v[12:15]
	v_mfma_f32_16x16x32_bf16 v[8:11], v[152:155], v[210:213], v[8:11]
	s_setprio 0
	s_setprio 1
	v_mfma_f32_16x16x32_bf16 v[52:55], v[166:169], v[182:185], v[52:55]
	v_mfma_f32_16x16x32_bf16 v[48:51], v[174:177], v[182:185], v[48:51]
	v_mfma_f32_16x16x32_bf16 v[36:39], v[166:169], v[190:193], v[36:39]
	v_mfma_f32_16x16x32_bf16 v[32:35], v[174:177], v[190:193], v[32:35]
	v_mfma_f32_16x16x32_bf16 v[20:23], v[166:169], v[198:201], v[20:23]
	v_mfma_f32_16x16x32_bf16 v[16:19], v[174:177], v[198:201], v[16:19]
	v_mfma_f32_16x16x32_bf16 v[4:7], v[166:169], v[206:209], v[4:7]
	v_mfma_f32_16x16x32_bf16 v[0:3], v[174:177], v[206:209], v[0:3]
	v_mfma_f32_16x16x32_bf16 v[52:55], v[170:173], v[186:189], v[52:55]
	v_mfma_f32_16x16x32_bf16 v[48:51], v[178:181], v[186:189], v[48:51]
	v_mfma_f32_16x16x32_bf16 v[36:39], v[170:173], v[194:197], v[36:39]
	v_mfma_f32_16x16x32_bf16 v[32:35], v[178:181], v[194:197], v[32:35]
	v_mfma_f32_16x16x32_bf16 v[20:23], v[170:173], v[202:205], v[20:23]
	v_mfma_f32_16x16x32_bf16 v[16:19], v[178:181], v[202:205], v[16:19]
	v_mfma_f32_16x16x32_bf16 v[4:7], v[170:173], v[210:213], v[4:7]
	v_mfma_f32_16x16x32_bf16 v[0:3], v[178:181], v[210:213], v[0:3]
	s_setprio 0
	s_barrier
	s_add_i32 s65, s65, 2
	s_add_u32 s12, s12, 0x100
	s_addc_u32 s13, s13, 0
	s_add_u32 s62, s62, 0x100
	s_addc_u32 s63, s63, 0
	s_cmp_gt_u32 s65, 29
	s_cbranch_scc0 .LBB0_1309
	s_and_b64 vcc, exec, s[26:27]
	s_cbranch_vccz .LBB0_1312
	s_barrier

; #define PG8_STAGE(bufoff, gbase, voff) do { _Pragma("unroll") for (int _i = 0; _i < 2; ++_i) \
;         __builtin_amdgcn_global_load_lds((const unsigned*)((const char*)(gbase) + (voff)[_i]), (PG8_LAS unsigned*)(lds + (bufoff) + ldsw + _i * 8192), 16, 0, 0); } while (0)
; #define PG8_LDA(dst, b, h) do { _Pragma("unroll") for (int m = 0; m < 4; ++m) _Pragma("unroll") for (int k = 0; k < 2; ++k) dst[m][k] = *(const PG8_LAS bf16x8*)(lds + PG8_SA(b, h) + aoff + m * 2048 + k * 1024); } while (0)
; #define PG8_LDB(dst, b, h) do { _Pragma("unroll") for (int n = 0; n < 2; ++n) _Pragma("unroll") for (int k = 0; k < 2; ++k) dst[n][k] = *(const PG8_LAS bf16x8*)(lds + PG8_SB(b, h) + boff + n * 2048 + k * 1024); } while (0)
; #define PG8_WAIT_V(n) asm volatile("s_waitcnt vmcnt(" #n ")" ::: "memory")
; #define PG8_WAIT_L(n) asm volatile("s_waitcnt lgkmcnt(" #n ")" ::: "memory")
; template <class Epi, class Sched, bool ALIGN_EPI = false, bool SP2 = false>
; __device__ __forceinline__ void gemm_phase(PG8_LAS unsigned char* lds, const Gemm g, const Sched& S, const Epi& E) {
;     ...
;         for (int t = 0; t < nt; t += 2) {
;             const bool last = (t == nt - 2);
;             if constexpr (Epi::HAS_MID) { if (t == E.mid_t) E.mid(acc, cur, wr, wc, fr, fq); }
;             const char* a1 = cA + (size_t)(t + 1) * kstep;
;             const char* a2 = last ? nA : cA + (size_t)(t + 2) * kstep; const char* b2 = last ? nB : cB + (size_t)(t + 2) * kstep;
;             const char* a3 = a2 + kstep; const char* b3 = b2 + kstep;
;             if (last && has_next) S.a_ready(nxt);
;             if constexpr (SP2) {
;             PG8_LDB(B0, 0, 0); PG8_LDB(B1, 0, 1); PG8_SCHED; PG8_LDA(At, 0, 0); PG8_STAGE(PG8_SA(1, 1), a1 + hstepA, voffA);
;             PG8_WAIT_V(8); PG8_WAIT_L(0); PG8_BAR; PG8_MMA(0, 0, At, B0); PG8_MMA(0, 1, At, B1); PG8_BAR; PG8_SCHED;
;             PG8_LDA(At, 0, 1); PG8_STAGE(PG8_SB(0, 0), b2, voffB); PG8_STAGE(PG8_SB(0, 1), b2 + hstepB, voffB); PG8_STAGE(PG8_SA(0, 0), a2, voffA);
;             PG8_WAIT_V(8); PG8_WAIT_L(0); PG8_BAR; PG8_MMA(1, 0, At, B0); PG8_MMA(1, 1, At, B1); PG8_BAR; PG8_SCHED;
;             PG8_LDB(B0, 1, 0); PG8_LDB(B1, 1, 1); PG8_SCHED; PG8_LDA(At, 1, 0); PG8_STAGE(PG8_SA(0, 1), a2 + hstepA, voffA);
;             PG8_WAIT_V(8); PG8_WAIT_L(0); PG8_BAR; PG8_MMA(0, 0, At, B0); PG8_MMA(0, 1, At, B1); PG8_BAR; PG8_SCHED;
.Lp7h_loop:
	ds_read_b128 v[144:147], v151
	ds_read_b128 v[156:159], v151 offset:1024
	ds_read_b128 v[160:163], v151 offset:2048
	ds_read_b128 v[164:167], v151 offset:3072
	ds_read_b128 v[168:171], v152
	ds_read_b128 v[172:175], v152 offset:1024
	ds_read_b128 v[176:179], v152 offset:2048
	ds_read_b128 v[180:183], v152 offset:3072
	s_add_u32 s34, s30, 0xfff80080
	s_addc_u32 s35, s31, -1
	s_cmp_eq_u32 s62, 28
	s_cselect_b32 s39, s21, s35
	s_cselect_b32 s38, s25, s34
	s_cselect_b32 s35, s23, s61
	s_cselect_b32 s34, s59, s60
	s_add_i32 m0, s6, 0xc000
	s_nop 0
	global_load_lds_dwordx4 v136, s[30:31]
	s_add_i32 m0, s6, 0xe000
	s_nop 0
	global_load_lds_dwordx4 v138, s[30:31]
	s_waitcnt vmcnt(6)
	s_waitcnt lgkmcnt(0)
	s_barrier
	s_setprio 1
	s_waitcnt lgkmcnt(0)
	v_mfma_f32_16x16x32_bf16 v[56:59], v[80:83], v[184:187], v[56:59]
	v_mfma_f32_16x16x32_bf16 v[48:51], v[88:91], v[184:187], v[48:51]
	v_mfma_f32_16x16x32_bf16 v[40:43], v[80:83], v[192:195], v[40:43]
	v_mfma_f32_16x16x32_bf16 v[32:35], v[88:91], v[192:195], v[32:35]
	v_mfma_f32_16x16x32_bf16 v[24:27], v[80:83], v[200:203], v[24:27]
	v_mfma_f32_16x16x32_bf16 v[16:19], v[88:91], v[200:203], v[16:19]
	v_mfma_f32_16x16x32_bf16 v[8:11], v[80:83], v[208:211], v[8:11]
	v_mfma_f32_16x16x32_bf16 v[0:3], v[88:91], v[208:211], v[0:3]
	v_mfma_f32_16x16x32_bf16 v[56:59], v[84:87], v[188:191], v[56:59]
	v_mfma_f32_16x16x32_bf16 v[48:51], v[92:95], v[188:191], v[48:51]
	v_mfma_f32_16x16x32_bf16 v[40:43], v[84:87], v[196:199], v[40:43]
	v_mfma_f32_16x16x32_bf16 v[32:35], v[92:95], v[196:199], v[32:35]
	v_mfma_f32_16x16x32_bf16 v[24:27], v[84:87], v[204:207], v[24:27]
	v_mfma_f32_16x16x32_bf16 v[16:19], v[92:95], v[204:207], v[16:19]
	v_mfma_f32_16x16x32_bf16 v[8:11], v[84:87], v[212:215], v[8:11]
	v_mfma_f32_16x16x32_bf16 v[0:3], v[92:95], v[212:215], v[0:3]
	s_setprio 0
	s_setprio 1
	s_setprio 0
	s_barrier
	s_add_i32 s63, s53, s4
	s_mov_b32 m0, s63
	ds_read_b128 v[184:187], v153 offset:16384
	ds_read_b128 v[188:191], v153 offset:17408
	ds_read_b128 v[192:195], v153 offset:18432
	ds_read_b128 v[196:199], v153 offset:19456
	ds_read_b128 v[200:203], v153 offset:20480
	ds_read_b128 v[204:207], v153 offset:21504
	ds_read_b128 v[208:211], v153 offset:22528
	ds_read_b128 v[212:215], v153 offset:23552
	global_load_lds_dwordx4 v132, s[34:35]
	s_add_i32 m0, s63, 0x2000
	s_add_u32 s64, s34, 0x80000
	s_addc_u32 s65, s35, 0
	s_add_i32 s63, s54, s4
	global_load_lds_dwordx4 v128, s[34:35]
	s_mov_b32 m0, s63
	s_nop 0
	global_load_lds_dwordx4 v132, s[64:65]
	s_add_i32 m0, s63, 0x2000
	s_nop 0
	global_load_lds_dwordx4 v128, s[64:65]
	s_waitcnt vmcnt(6)
	s_waitcnt lgkmcnt(0)
	s_barrier
	s_setprio 1
	s_waitcnt lgkmcnt(0)
	v_mfma_f32_16x16x32_bf16 v[60:63], v[144:147], v[184:187], v[60:63]
	v_mfma_f32_16x16x32_bf16 v[52:55], v[160:163], v[184:187], v[52:55]
	v_mfma_f32_16x16x32_bf16 v[44:47], v[144:147], v[192:195], v[44:47]
	v_mfma_f32_16x16x32_bf16 v[36:39], v[160:163], v[192:195], v[36:39]
	v_mfma_f32_16x16x32_bf16 v[28:31], v[144:147], v[200:203], v[28:31]
	v_mfma_f32_16x16x32_bf16 v[20:23], v[160:163], v[200:203], v[20:23]
	v_mfma_f32_16x16x32_bf16 v[12:15], v[144:147], v[208:211], v[12:15]
	v_mfma_f32_16x16x32_bf16 v[4:7], v[160:163], v[208:211], v[4:7]
	v_mfma_f32_16x16x32_bf16 v[60:63], v[156:159], v[188:191], v[60:63]
	v_mfma_f32_16x16x32_bf16 v[52:55], v[164:167], v[188:191], v[52:55]
	v_mfma_f32_16x16x32_bf16 v[44:47], v[156:159], v[196:199], v[44:47]
	v_mfma_f32_16x16x32_bf16 v[36:39], v[164:167], v[196:199], v[36:39]
	v_mfma_f32_16x16x32_bf16 v[28:31], v[156:159], v[204:207], v[28:31]
	v_mfma_f32_16x16x32_bf16 v[20:23], v[164:167], v[204:207], v[20:23]
	v_mfma_f32_16x16x32_bf16 v[12:15], v[156:159], v[212:215], v[12:15]
	v_mfma_f32_16x16x32_bf16 v[4:7], v[164:167], v[212:215], v[4:7]
	s_setprio 0
	s_setprio 1
	s_setprio 0
	s_barrier
	s_add_i32 s63, 0, 0x18000
	v_add_u32_e32 v155, s63, v150
	s_add_i32 s64, 0, 0x1c000
	ds_read_b128 v[64:67], v155
	ds_read_b128 v[68:71], v155 offset:1024
	ds_read_b128 v[72:75], v155 offset:2048
	ds_read_b128 v[76:79], v155 offset:3072
	v_add_u32_e32 v155, s64, v150
	ds_read_b128 v[80:83], v155
	ds_read_b128 v[84:87], v155 offset:1024
	ds_read_b128 v[88:91], v155 offset:2048
	ds_read_b128 v[92:95], v155 offset:3072
	s_add_u32 s38, s38, 0x80000
	s_addc_u32 s39, s39, 0
	s_mov_b32 m0, s41
	s_nop 0
	global_load_lds_dwordx4 v134, s[38:39]
	s_mov_b32 m0, s42
	s_nop 0
	global_load_lds_dwordx4 v130, s[38:39]
	s_waitcnt vmcnt(6)
	s_waitcnt lgkmcnt(0)
	s_barrier
; #define PG8_STAGE(bufoff, gbase, voff) do { _Pragma("unroll") for (int _i = 0; _i < 2; ++_i) \
;         __builtin_amdgcn_global_load_lds((const unsigned*)((const char*)(gbase) + (voff)[_i]), (PG8_LAS unsigned*)(lds + (bufoff) + ldsw + _i * 8192), 16, 0, 0); } while (0)
; #define PG8_LDA(dst, b, h) do { _Pragma("unroll") for (int m = 0; m < 4; ++m) _Pragma("unroll") for (int k = 0; k < 2; ++k) dst[m][k] = *(const PG8_LAS bf16x8*)(lds + PG8_SA(b, h) + aoff + m * 2048 + k * 1024); } while (0)
; #define PG8_LDB(dst, b, h) do { _Pragma("unroll") for (int n = 0; n < 2; ++n) _Pragma("unroll") for (int k = 0; k < 2; ++k) dst[n][k] = *(const PG8_LAS bf16x8*)(lds + PG8_SB(b, h) + boff + n * 2048 + k * 1024); } while (0)
; #define PG8_MMA(ai, bj, At, Bt) do { __builtin_amdgcn_s_setprio(1); _Pragma("unroll") for (int m = 0; m < 4; ++m) _Pragma("unroll") for (int n = 0; n < 2; ++n) _Pragma("unroll") for (int k = 0; k < 2; ++k) \
;         acc[ai][bj][m][n] = __builtin_amdgcn_mfma_f32_16x16x32_bf16(Bt[n][k], At[m][k], acc[ai][bj][m][n], 0, 0, 0); __builtin_amdgcn_s_setprio(0); } while (0)
; #define PG8_WAIT_V(n) asm volatile("s_waitcnt vmcnt(" #n ")" ::: "memory")
; #define PG8_WAIT_L(n) asm volatile("s_waitcnt lgkmcnt(" #n ")" ::: "memory")
; #define PG8_BAR __builtin_amdgcn_s_barrier()
; #define PG8_SCHED __builtin_amdgcn_sched_barrier(0)
; template <class Epi, class Sched, bool ALIGN_EPI = false, bool SP2 = false>
; __device__ __forceinline__ void gemm_phase(PG8_LAS unsigned char* lds, const Gemm g, const Sched& S, const Epi& E) {
;     ...
;             PG8_LDB(B0, 1, 0); PG8_LDB(B1, 1, 1); PG8_SCHED; PG8_LDA(At, 1, 0); PG8_STAGE(PG8_SA(0, 1), a2 + hstepA, voffA);
;             PG8_WAIT_V(8); PG8_WAIT_L(0); PG8_BAR; PG8_MMA(0, 0, At, B0); PG8_MMA(0, 1, At, B1); PG8_BAR; PG8_SCHED;
;             PG8_LDA(At, 1, 1); PG8_STAGE(PG8_SB(1, 0), b3, voffB); PG8_STAGE(PG8_SB(1, 1), b3 + hstepB, voffB); PG8_STAGE(PG8_SA(1, 0), a3, voffA);
;             PG8_WAIT_V(8); PG8_WAIT_L(0); PG8_BAR; PG8_MMA(1, 0, At, B0); PG8_MMA(1, 1, At, B1); PG8_BAR; PG8_SCHED;
	s_setprio 1
	s_waitcnt lgkmcnt(0)
	v_mfma_f32_16x16x32_bf16 v[56:59], v[168:171], v[184:187], v[56:59]
	v_mfma_f32_16x16x32_bf16 v[48:51], v[176:179], v[184:187], v[48:51]
	v_mfma_f32_16x16x32_bf16 v[40:43], v[168:171], v[192:195], v[40:43]
	v_mfma_f32_16x16x32_bf16 v[32:35], v[176:179], v[192:195], v[32:35]
	v_mfma_f32_16x16x32_bf16 v[24:27], v[168:171], v[200:203], v[24:27]
	v_mfma_f32_16x16x32_bf16 v[16:19], v[176:179], v[200:203], v[16:19]
	v_mfma_f32_16x16x32_bf16 v[8:11], v[168:171], v[208:211], v[8:11]
	v_mfma_f32_16x16x32_bf16 v[0:3], v[176:179], v[208:211], v[0:3]
	v_mfma_f32_16x16x32_bf16 v[56:59], v[172:175], v[188:191], v[56:59]
	v_mfma_f32_16x16x32_bf16 v[48:51], v[180:183], v[188:191], v[48:51]
	v_mfma_f32_16x16x32_bf16 v[40:43], v[172:175], v[196:199], v[40:43]
	v_mfma_f32_16x16x32_bf16 v[32:35], v[180:183], v[196:199], v[32:35]
	v_mfma_f32_16x16x32_bf16 v[24:27], v[172:175], v[204:207], v[24:27]
	v_mfma_f32_16x16x32_bf16 v[16:19], v[180:183], v[204:207], v[16:19]
	v_mfma_f32_16x16x32_bf16 v[8:11], v[172:175], v[212:215], v[8:11]
	v_mfma_f32_16x16x32_bf16 v[0:3], v[180:183], v[212:215], v[0:3]
	s_setprio 0
	s_setprio 1
	s_setprio 0
	s_barrier
	s_add_i32 s38, s63, s4
	s_add_u32 s98, s34, 0x80
	s_addc_u32 s99, s35, 0
	s_mov_b32 m0, s38
	ds_read_b128 v[184:187], v153 offset:49152
	ds_read_b128 v[188:191], v153 offset:50176
	ds_read_b128 v[192:195], v153 offset:51200
	ds_read_b128 v[196:199], v153 offset:52224
	ds_read_b128 v[200:203], v153 offset:53248
	ds_read_b128 v[204:207], v153 offset:54272
	ds_read_b128 v[208:211], v153 offset:55296
	ds_read_b128 v[212:215], v153 offset:56320
	global_load_lds_dwordx4 v132, s[98:99]
	s_add_i32 m0, s38, 0x2000
	s_add_u32 s34, s34, 0x80080
	s_addc_u32 s35, s35, 0
	s_add_i32 s38, s64, s4
	global_load_lds_dwordx4 v128, s[98:99]
	s_mov_b32 m0, s38
	s_nop 0
	global_load_lds_dwordx4 v132, s[34:35]
	s_add_i32 m0, s38, 0x2000
	s_nop 0
	global_load_lds_dwordx4 v128, s[34:35]
	s_waitcnt vmcnt(6)
	s_waitcnt lgkmcnt(0)
	s_barrier
	s_setprio 1
	s_waitcnt lgkmcnt(0)
	v_mfma_f32_16x16x32_bf16 v[60:63], v[64:67], v[184:187], v[60:63]
	v_mfma_f32_16x16x32_bf16 v[52:55], v[72:75], v[184:187], v[52:55]
	v_mfma_f32_16x16x32_bf16 v[44:47], v[64:67], v[192:195], v[44:47]
	v_mfma_f32_16x16x32_bf16 v[36:39], v[72:75], v[192:195], v[36:39]
	v_mfma_f32_16x16x32_bf16 v[28:31], v[64:67], v[200:203], v[28:31]
	v_mfma_f32_16x16x32_bf16 v[20:23], v[72:75], v[200:203], v[20:23]
	v_mfma_f32_16x16x32_bf16 v[12:15], v[64:67], v[208:211], v[12:15]
	v_mfma_f32_16x16x32_bf16 v[4:7], v[72:75], v[208:211], v[4:7]
	v_mfma_f32_16x16x32_bf16 v[60:63], v[68:71], v[188:191], v[60:63]
	v_mfma_f32_16x16x32_bf16 v[52:55], v[76:79], v[188:191], v[52:55]
	v_mfma_f32_16x16x32_bf16 v[44:47], v[68:71], v[196:199], v[44:47]
	v_mfma_f32_16x16x32_bf16 v[36:39], v[76:79], v[196:199], v[36:39]
	v_mfma_f32_16x16x32_bf16 v[28:31], v[68:71], v[204:207], v[28:31]
	v_mfma_f32_16x16x32_bf16 v[20:23], v[76:79], v[204:207], v[20:23]
	v_mfma_f32_16x16x32_bf16 v[12:15], v[68:71], v[212:215], v[12:15]
	v_mfma_f32_16x16x32_bf16 v[4:7], v[76:79], v[212:215], v[4:7]
	s_setprio 0
	s_setprio 1
	s_setprio 0
	s_barrier
	s_add_i32 s62, s62, 2
	s_add_u32 s30, s30, 0x100
	s_addc_u32 s31, s31, 0
	s_add_u32 s60, s60, 0x100
	s_addc_u32 s61, s61, 0
	s_cmp_gt_u32 s62, 29
	s_cbranch_scc0 .Lp7h_loop
	v_mfma_f32_16x16x32_bf16 v[56:59], v[80:83], v[184:187], v[56:59]
	v_mfma_f32_16x16x32_bf16 v[48:51], v[88:91], v[184:187], v[48:51]
	v_mfma_f32_16x16x32_bf16 v[40:43], v[80:83], v[192:195], v[40:43]
	v_mfma_f32_16x16x32_bf16 v[32:35], v[88:91], v[192:195], v[32:35]
	v_mfma_f32_16x16x32_bf16 v[24:27], v[80:83], v[200:203], v[24:27]
	v_mfma_f32_16x16x32_bf16 v[16:19], v[88:91], v[200:203], v[16:19]
	v_mfma_f32_16x16x32_bf16 v[8:11], v[80:83], v[208:211], v[8:11]
	v_mfma_f32_16x16x32_bf16 v[0:3], v[88:91], v[208:211], v[0:3]
	v_mfma_f32_16x16x32_bf16 v[56:59], v[84:87], v[188:191], v[56:59]
	v_mfma_f32_16x16x32_bf16 v[48:51], v[92:95], v[188:191], v[48:51]
	v_mfma_f32_16x16x32_bf16 v[40:43], v[84:87], v[196:199], v[40:43]
	v_mfma_f32_16x16x32_bf16 v[32:35], v[92:95], v[196:199], v[32:35]
	v_mfma_f32_16x16x32_bf16 v[24:27], v[84:87], v[204:207], v[24:27]
	v_mfma_f32_16x16x32_bf16 v[16:19], v[92:95], v[204:207], v[16:19]
	v_mfma_f32_16x16x32_bf16 v[8:11], v[84:87], v[212:215], v[8:11]
	v_mfma_f32_16x16x32_bf16 v[0:3], v[92:95], v[212:215], v[0:3]
	s_nop 15
	s_nop 15
	s_branch .Lp7_after_loop
